# P0 weight conversion: in 5 of the 12 loops the gain wait no longer drains the next item's 32 prefetch loads (counted vmcnt 33/32 + head vmcnt(4)); on top of mnk + saddr
# baseline (speedup 1.0000x reference)
.LBB0_772:
	s_waitcnt lgkmcnt(0)
	ds_read2_b32 v[74:75], v33 offset0:231 offset1:239
	ds_read2_b32 v[76:77], v33 offset0:165 offset1:173
	ds_read2_b32 v[78:79], v33 offset0:198 offset1:206
	ds_read2_b32 v[80:81], v33 offset0:132 offset1:140
	ds_read2_b32 v[84:85], v33 offset0:99 offset1:107
	ds_read2_b32 v[86:87], v33 offset0:33 offset1:41
	ds_read2_b32 v[88:89], v33 offset0:66 offset1:74
	ds_read2_b32 v[92:93], v33 offset1:8
	s_waitcnt vmcnt(33)
	v_mov_b32_e32 v82, v39
	v_mov_b32_e32 v83, v41
	v_mov_b32_e32 v39, v40
	s_waitcnt lgkmcnt(4)
	v_mov_b32_e32 v40, v80
	v_mov_b32_e32 v41, v78
	s_waitcnt vmcnt(32)
	v_mov_b32_e32 v90, v35
	v_mov_b32_e32 v91, v37
	v_mov_b32_e32 v35, v36
	s_waitcnt lgkmcnt(0)
	v_mov_b32_e32 v36, v92
	v_mov_b32_e32 v37, v88
	v_mov_b32_e32 v70, v76
	v_mov_b32_e32 v71, v74
	v_pk_mul_f32 v[40:41], v[38:39], v[40:41]
	v_mov_b32_e32 v72, v86
	v_mov_b32_e32 v73, v84
	v_pk_mul_f32 v[36:37], v[34:35], v[36:37]
	s_lshl_b32 s8, s69, 12
	v_pk_mul_f32 v[70:71], v[82:83], v[70:71]
	v_pk_mul_f32 v[72:73], v[90:91], v[72:73]
	v_bfe_u32 v69, v36, 16, 1
	v_bfe_u32 v74, v37, 16, 1
	v_bfe_u32 v76, v40, 16, 1
	v_bfe_u32 v78, v41, 16, 1
	s_sub_i32 s8, s68, s8
	v_add3_u32 v41, v41, v78, s63
	v_add3_u32 v40, v40, v76, s63
	v_add3_u32 v37, v37, v74, s63
	v_add3_u32 v36, v36, v69, s63
	v_bfe_u32 v74, v70, 16, 1
	v_bfe_u32 v76, v73, 16, 1
	v_bfe_u32 v78, v72, 16, 1
	s_ashr_i32 s9, s8, 31
	v_lshrrev_b32_e32 v36, 16, v36
	v_lshrrev_b32_e32 v37, 16, v37
	v_lshrrev_b32_e32 v40, 16, v40
	v_bfe_u32 v69, v71, 16, 1
	v_add3_u32 v78, v72, v78, s63
	v_add3_u32 v76, v73, v76, s63
	v_add3_u32 v70, v70, v74, s63
	v_add3_u32 v69, v71, v69, s63
	v_and_or_b32 v72, v70, s65, v40
	v_and_or_b32 v71, v76, s65, v37
	v_and_or_b32 v70, v78, s65, v36
	v_mov_b32_e32 v37, s9
	v_or_b32_e32 v36, s8, v44
	v_lshl_add_u64 v[62:63], s[86:87], 1, v[54:55]
	v_lshrrev_b32_e32 v41, 16, v41
	v_lshlrev_b64 v[36:37], 13, v[36:37]
	v_and_or_b32 v73, v69, s65, v41
	v_lshl_add_u64 v[36:37], v[62:63], 0, v[36:37]
	v_mov_b32_e32 v88, v93
	global_store_dwordx4 v[36:37], v[70:73], off
	v_mov_b32_e32 v74, v77
	v_mov_b32_e32 v78, v81
	v_pk_mul_f32 v[72:73], v[34:35], v[88:89]
	v_pk_mul_f32 v[36:37], v[82:83], v[74:75]
	v_pk_mul_f32 v[40:41], v[38:39], v[78:79]
	v_bfe_u32 v74, v73, 16, 1
	v_bfe_u32 v69, v72, 16, 1
	v_bfe_u32 v75, v40, 16, 1
	v_bfe_u32 v76, v41, 16, 1
	v_add3_u32 v73, v73, v74, s63
	v_mov_b32_e32 v84, v87
	v_add3_u32 v41, v41, v76, s63
	v_add3_u32 v40, v40, v75, s63
	v_add3_u32 v69, v72, v69, s63
	v_lshrrev_b32_e32 v74, 16, v73
	v_bfe_u32 v72, v37, 16, 1
	v_bfe_u32 v73, v36, 16, 1
	v_pk_mul_f32 v[70:71], v[90:91], v[84:85]
	v_lshrrev_b32_e32 v40, 16, v40
	v_lshrrev_b32_e32 v41, 16, v41
	v_add3_u32 v36, v36, v73, s63
	v_add3_u32 v37, v37, v72, s63
	v_bfe_u32 v75, v71, 16, 1
	v_bfe_u32 v76, v70, 16, 1
	v_and_or_b32 v73, v37, s65, v41
	v_and_or_b32 v72, v36, s65, v40
	v_mov_b32_e32 v37, s9
	v_or_b32_e32 v36, s8, v56
	v_lshrrev_b32_e32 v69, 16, v69
	v_add3_u32 v70, v70, v76, s63
	v_add3_u32 v71, v71, v75, s63
	v_lshlrev_b64 v[36:37], 13, v[36:37]
	v_and_or_b32 v71, v71, s65, v74
	v_and_or_b32 v70, v70, s65, v69
	v_lshl_add_u64 v[36:37], v[62:63], 0, v[36:37]
	ds_read2_b32 v[40:41], v33 offset0:181 offset1:189
	ds_read2_b32 v[74:75], v33 offset0:247 offset1:255
	global_store_dwordx4 v[36:37], v[70:73], off
	ds_read2_b32 v[36:37], v33 offset0:148 offset1:156
	ds_read2_b32 v[76:77], v33 offset0:214 offset1:222
	ds_read2_b32 v[78:79], v33 offset0:49 offset1:57
	ds_read2_b32 v[80:81], v33 offset0:115 offset1:123
	ds_read2_b32 v[84:85], v33 offset0:16 offset1:24
	ds_read2_b32 v[86:87], v33 offset0:82 offset1:90
	s_waitcnt lgkmcnt(7)
	v_mov_b32_e32 v70, v40
	s_waitcnt lgkmcnt(5)
	v_mov_b32_e32 v72, v36
	s_waitcnt lgkmcnt(4)
	v_mov_b32_e32 v73, v76
	v_pk_mul_f32 v[72:73], v[38:39], v[72:73]
	s_waitcnt lgkmcnt(1)
	v_mov_b32_e32 v92, v84
	s_waitcnt lgkmcnt(0)
	v_mov_b32_e32 v93, v86
	v_mov_b32_e32 v71, v74
	v_mov_b32_e32 v88, v78
	v_mov_b32_e32 v89, v80
	v_pk_mul_f32 v[92:93], v[34:35], v[92:93]
	v_bfe_u32 v74, v73, 16, 1
	v_pk_mul_f32 v[70:71], v[82:83], v[70:71]
	v_pk_mul_f32 v[88:89], v[90:91], v[88:89]
	v_bfe_u32 v40, v93, 16, 1
	v_bfe_u32 v69, v72, 16, 1
	v_add3_u32 v73, v73, v74, s63
	v_bfe_u32 v36, v92, 16, 1
	v_add3_u32 v69, v72, v69, s63
	v_add3_u32 v40, v93, v40, s63
	v_lshrrev_b32_e32 v72, 16, v73
	v_bfe_u32 v73, v71, 16, 1
	v_bfe_u32 v76, v89, 16, 1
	v_bfe_u32 v78, v88, 16, 1
	v_add3_u32 v36, v92, v36, s63
	v_lshrrev_b32_e32 v40, 16, v40
	v_bfe_u32 v74, v70, 16, 1
	v_add3_u32 v78, v88, v78, s63
	v_add3_u32 v76, v89, v76, s63
	v_add3_u32 v71, v71, v73, s63
	v_mov_b32_e32 v89, s9
	v_or_b32_e32 v88, s8, v58
	v_lshrrev_b32_e32 v36, 16, v36
	v_lshrrev_b32_e32 v69, 16, v69
	v_add3_u32 v70, v70, v74, s63
	v_and_or_b32 v73, v71, s65, v72
	v_and_or_b32 v71, v76, s65, v40
	v_lshlrev_b64 v[88:89], 13, v[88:89]
	v_mov_b32_e32 v76, v37
	v_mov_b32_e32 v86, v85
	v_and_or_b32 v72, v70, s65, v69
	v_and_or_b32 v70, v78, s65, v36
	v_lshl_add_u64 v[88:89], v[62:63], 0, v[88:89]
	v_pk_mul_f32 v[36:37], v[38:39], v[76:77]
	v_mov_b32_e32 v80, v79
	v_pk_mul_f32 v[34:35], v[34:35], v[86:87]
	global_store_dwordx4 v[88:89], v[70:73], off
	v_pk_mul_f32 v[38:39], v[90:91], v[80:81]
	v_bfe_u32 v69, v34, 16, 1
	v_bfe_u32 v70, v35, 16, 1
	v_bfe_u32 v71, v36, 16, 1
	v_bfe_u32 v72, v37, 16, 1
	v_mov_b32_e32 v74, v41
	v_add3_u32 v37, v37, v72, s63
	v_add3_u32 v36, v36, v71, s63
	v_add3_u32 v35, v35, v70, s63
	v_add3_u32 v34, v34, v69, s63
	v_bfe_u32 v71, v39, 16, 1
	v_bfe_u32 v72, v38, 16, 1
	v_pk_mul_f32 v[40:41], v[82:83], v[74:75]
	v_lshrrev_b32_e32 v34, 16, v34
	v_lshrrev_b32_e32 v35, 16, v35
	v_add3_u32 v38, v38, v72, s63
	v_add3_u32 v39, v39, v71, s63
	v_bfe_u32 v69, v41, 16, 1
	v_bfe_u32 v70, v40, 16, 1
	v_and_or_b32 v35, v39, s65, v35
	v_and_or_b32 v34, v38, s65, v34
	v_mov_b32_e32 v39, s9
	v_or_b32_e32 v38, s8, v60
	v_lshrrev_b32_e32 v36, 16, v36
	v_lshrrev_b32_e32 v37, 16, v37
	v_add3_u32 v40, v40, v70, s63
	v_add3_u32 v41, v41, v69, s63
	v_lshlrev_b64 v[38:39], 13, v[38:39]
	v_and_or_b32 v37, v41, s65, v37
	v_and_or_b32 v36, v40, s65, v36
	v_lshl_add_u64 v[38:39], v[62:63], 0, v[38:39]
	global_store_dwordx4 v[38:39], v[34:37], off
	s_waitcnt lgkmcnt(0)
	s_andn2_b64 vcc, exec, s[84:85]
	s_mov_b32 s68, s67
	s_cbranch_vccz .LBB0_840
.LBB0_773:
	s_ashr_i32 s8, s66, 31
	s_lshr_b32 s8, s8, 25
	s_add_i32 s8, s66, s8
	s_ashr_i32 s69, s8, 7
	s_lshl_b32 s86, s69, 6
	s_ashr_i32 s87, s86, 31
	s_waitcnt vmcnt(4)
	ds_write2_b32 v47, v2, v1 offset1:66
	ds_write2_b32 v47, v4, v3 offset0:132 offset1:198
	ds_write2_b32 v49, v6, v5 offset0:8 offset1:74
	ds_write2_b32 v49, v8, v7 offset0:140 offset1:206
	ds_write2_b32 v61, v10, v9 offset0:16 offset1:82
	ds_write2_b32 v61, v12, v11 offset0:148 offset1:214
	ds_write2_b32 v64, v14, v13 offset0:24 offset1:90
	ds_write2_b32 v64, v16, v15 offset0:156 offset1:222
	ds_write2_b32 v65, v18, v17 offset0:32 offset1:98
	ds_write2_b32 v65, v20, v19 offset0:164 offset1:230
	ds_write2_b32 v66, v22, v21 offset0:40 offset1:106
	ds_write2_b32 v66, v24, v23 offset0:172 offset1:238
	ds_write2_b32 v67, v26, v25 offset0:48 offset1:114
	ds_write2_b32 v67, v28, v27 offset0:180 offset1:246
	ds_write2_b32 v68, v30, v29 offset0:56 offset1:122
	ds_write2_b32 v68, v32, v31 offset0:188 offset1:254
	v_lshl_add_u64 v[34:35], s[86:87], 2, v[52:53]
	global_load_dwordx4 v[38:41], v[34:35], off offset:16
	s_nop 0
	global_load_dwordx4 v[34:37], v[34:35], off
	s_add_i32 s66, s66, s58
	s_cmpk_gt_i32 s66, 0x1fff
	s_mov_b64 s[8:9], -1
	s_cselect_b64 s[84:85], -1, 0
	s_cmpk_lt_i32 s66, 0x2000
	s_cbranch_scc1 .LBB0_775
	s_add_i32 s67, s68, s35
	s_mov_b64 s[8:9], 0

.Lcvt_last_4:
	s_waitcnt vmcnt(0)
	s_branch .LBB0_772

.LBB0_909:
	s_lshl_b32 s8, s67, 7
	s_sub_i32 s66, s66, s8
	s_waitcnt lgkmcnt(0)
	s_bfe_i32 s8, s66, 0x80000
	s_bfe_u32 s8, s8, 0x2000d
	ds_read2_b32 v[72:73], v33 offset0:231 offset1:239
	ds_read2_b32 v[74:75], v33 offset0:165 offset1:173
	ds_read2_b32 v[76:77], v33 offset0:198 offset1:206
	ds_read2_b32 v[78:79], v33 offset0:132 offset1:140
	ds_read2_b32 v[82:83], v33 offset0:99 offset1:107
	ds_read2_b32 v[84:85], v33 offset0:33 offset1:41
	ds_read2_b32 v[86:87], v33 offset0:66 offset1:74
	ds_read2_b32 v[90:91], v33 offset1:8
	s_add_i32 s8, s66, s8
	s_lshl_b32 s66, s66, 5
	s_sext_i32_i16 s67, s66
	s_bfe_u32 s67, s67, 0x70018
	s_sext_i32_i8 s8, s8
	s_add_i32 s67, s66, s67
	s_lshr_b32 s8, s8, 2
	s_and_b32 s67, s67, 0xff80
	s_waitcnt vmcnt(33)
	v_mov_b32_e32 v80, v39
	v_mov_b32_e32 v81, v41
	v_mov_b32_e32 v39, v40
	s_waitcnt lgkmcnt(4)
	v_mov_b32_e32 v40, v78
	v_mov_b32_e32 v41, v76
	s_waitcnt vmcnt(32)
	v_mov_b32_e32 v88, v35
	v_mov_b32_e32 v89, v37
	v_mov_b32_e32 v35, v36
	s_waitcnt lgkmcnt(0)
	v_mov_b32_e32 v36, v90
	v_mov_b32_e32 v37, v86
	s_bfe_i64 s[8:9], s[8:9], 0x100000
	s_sub_i32 s66, s66, s67
	v_mov_b32_e32 v68, v74
	v_mov_b32_e32 v69, v72
	v_pk_mul_f32 v[40:41], v[38:39], v[40:41]
	v_mov_b32_e32 v70, v84
	v_mov_b32_e32 v71, v82
	v_pk_mul_f32 v[36:37], v[34:35], v[36:37]
	s_bfe_i64 s[66:67], s[66:67], 0x100000
	s_lshl_b64 s[8:9], s[8:9], 8
	v_pk_mul_f32 v[68:69], v[80:81], v[68:69]
	v_pk_mul_f32 v[70:71], v[88:89], v[70:71]
	v_bfe_u32 v72, v36, 16, 1
	v_bfe_u32 v74, v37, 16, 1
	v_bfe_u32 v76, v40, 16, 1
	v_bfe_u32 v78, v41, 16, 1
	s_add_u32 s8, s8, s66
	v_add3_u32 v41, v41, v78, s62
	v_add3_u32 v40, v40, v76, s62
	v_add3_u32 v37, v37, v74, s62
	v_add3_u32 v36, v36, v72, s62
	v_bfe_u32 v72, v69, 16, 1
	v_bfe_u32 v74, v68, 16, 1
	v_bfe_u32 v76, v71, 16, 1
	v_bfe_u32 v78, v70, 16, 1
	s_addc_u32 s9, s9, s67
	v_lshrrev_b32_e32 v36, 16, v36
	v_lshrrev_b32_e32 v37, 16, v37
	v_lshrrev_b32_e32 v40, 16, v40
	v_lshrrev_b32_e32 v41, 16, v41
	v_add3_u32 v78, v70, v78, s62
	v_add3_u32 v76, v71, v76, s62
	v_add3_u32 v68, v68, v74, s62
	v_add3_u32 v69, v69, v72, s62
	v_and_or_b32 v71, v69, s63, v41
	v_and_or_b32 v70, v68, s63, v40
	v_and_or_b32 v69, v76, s63, v37
	v_and_or_b32 v68, v78, s63, v36
	v_mov_b32_e32 v37, s9
	v_or_b32_e32 v36, s8, v44
	v_lshl_add_u64 v[62:63], s[90:91], 1, v[54:55]
	v_lshlrev_b64 v[36:37], 13, v[36:37]
	v_lshl_add_u64 v[36:37], v[62:63], 0, v[36:37]
	v_mov_b32_e32 v86, v91
	global_store_dwordx4 v[36:37], v[68:71], off
	v_mov_b32_e32 v72, v75
	v_mov_b32_e32 v76, v79
	v_pk_mul_f32 v[70:71], v[34:35], v[86:87]
	v_pk_mul_f32 v[36:37], v[80:81], v[72:73]
	v_pk_mul_f32 v[40:41], v[38:39], v[76:77]
	v_bfe_u32 v72, v70, 16, 1
	v_bfe_u32 v73, v71, 16, 1
	v_bfe_u32 v74, v40, 16, 1
	v_bfe_u32 v75, v41, 16, 1
	v_add3_u32 v71, v71, v73, s62
	v_add3_u32 v70, v70, v72, s62
	v_mov_b32_e32 v82, v85
	v_add3_u32 v41, v41, v75, s62
	v_add3_u32 v40, v40, v74, s62
	v_lshrrev_b32_e32 v72, 16, v70
	v_lshrrev_b32_e32 v73, 16, v71
	v_bfe_u32 v70, v37, 16, 1
	v_bfe_u32 v71, v36, 16, 1
	v_pk_mul_f32 v[68:69], v[88:89], v[82:83]
	v_lshrrev_b32_e32 v40, 16, v40
	v_lshrrev_b32_e32 v41, 16, v41
	v_add3_u32 v36, v36, v71, s62
	v_add3_u32 v37, v37, v70, s62
	v_bfe_u32 v74, v69, 16, 1
	v_bfe_u32 v75, v68, 16, 1
	v_and_or_b32 v71, v37, s63, v41
	v_and_or_b32 v70, v36, s63, v40
	v_mov_b32_e32 v37, s9
	v_or_b32_e32 v36, s8, v56
	v_add3_u32 v68, v68, v75, s62
	v_add3_u32 v69, v69, v74, s62
	v_lshlrev_b64 v[36:37], 13, v[36:37]
	v_and_or_b32 v69, v69, s63, v73
	v_and_or_b32 v68, v68, s63, v72
	v_lshl_add_u64 v[36:37], v[62:63], 0, v[36:37]
	ds_read2_b32 v[40:41], v33 offset0:181 offset1:189
	ds_read2_b32 v[72:73], v33 offset0:247 offset1:255
	global_store_dwordx4 v[36:37], v[68:71], off
	ds_read2_b32 v[36:37], v33 offset0:148 offset1:156
	ds_read2_b32 v[74:75], v33 offset0:214 offset1:222
	ds_read2_b32 v[76:77], v33 offset0:49 offset1:57
	ds_read2_b32 v[78:79], v33 offset0:115 offset1:123
	ds_read2_b32 v[82:83], v33 offset0:16 offset1:24
	ds_read2_b32 v[84:85], v33 offset0:82 offset1:90
	s_waitcnt lgkmcnt(7)
	v_mov_b32_e32 v68, v40
	s_waitcnt lgkmcnt(5)
	v_mov_b32_e32 v70, v36
	s_waitcnt lgkmcnt(4)
	v_mov_b32_e32 v71, v74
	s_waitcnt lgkmcnt(3)
	v_mov_b32_e32 v86, v76
	s_waitcnt lgkmcnt(2)
	v_mov_b32_e32 v87, v78
	s_waitcnt lgkmcnt(1)
	v_mov_b32_e32 v90, v82
	s_waitcnt lgkmcnt(0)
	v_mov_b32_e32 v91, v84
	v_mov_b32_e32 v69, v72
	v_pk_mul_f32 v[70:71], v[38:39], v[70:71]
	v_pk_mul_f32 v[86:87], v[88:89], v[86:87]
	v_pk_mul_f32 v[90:91], v[34:35], v[90:91]
	v_pk_mul_f32 v[68:69], v[80:81], v[68:69]
	v_bfe_u32 v36, v90, 16, 1
	v_bfe_u32 v40, v91, 16, 1
	v_bfe_u32 v72, v70, 16, 1
	v_bfe_u32 v74, v71, 16, 1
	v_bfe_u32 v76, v87, 16, 1
	v_bfe_u32 v78, v86, 16, 1
	v_add3_u32 v71, v71, v74, s62
	v_add3_u32 v70, v70, v72, s62
	v_add3_u32 v40, v91, v40, s62
	v_add3_u32 v36, v90, v36, s62
	v_bfe_u32 v72, v69, 16, 1
	v_bfe_u32 v74, v68, 16, 1
	v_add3_u32 v78, v86, v78, s62
	v_add3_u32 v76, v87, v76, s62
	v_mov_b32_e32 v87, s9
	v_or_b32_e32 v86, s8, v58
	v_lshrrev_b32_e32 v36, 16, v36
	v_lshrrev_b32_e32 v40, 16, v40
	v_lshrrev_b32_e32 v70, 16, v70
	v_lshrrev_b32_e32 v71, 16, v71
	v_add3_u32 v68, v68, v74, s62
	v_add3_u32 v69, v69, v72, s62
	v_lshlrev_b64 v[86:87], 13, v[86:87]
	v_mov_b32_e32 v74, v37
	v_mov_b32_e32 v84, v83
	v_and_or_b32 v71, v69, s63, v71
	v_and_or_b32 v70, v68, s63, v70
	v_and_or_b32 v69, v76, s63, v40
	v_and_or_b32 v68, v78, s63, v36
	v_lshl_add_u64 v[86:87], v[62:63], 0, v[86:87]
	v_pk_mul_f32 v[36:37], v[38:39], v[74:75]
	v_mov_b32_e32 v78, v77
	v_pk_mul_f32 v[34:35], v[34:35], v[84:85]
	global_store_dwordx4 v[86:87], v[68:71], off
	v_pk_mul_f32 v[38:39], v[88:89], v[78:79]
	v_mov_b32_e32 v72, v41
	v_bfe_u32 v68, v34, 16, 1
	v_bfe_u32 v69, v35, 16, 1
	v_bfe_u32 v70, v36, 16, 1
	v_bfe_u32 v71, v37, 16, 1
	v_add3_u32 v37, v37, v71, s62
	v_add3_u32 v36, v36, v70, s62
	v_add3_u32 v35, v35, v69, s62
	v_add3_u32 v34, v34, v68, s62
	v_bfe_u32 v70, v39, 16, 1
	v_bfe_u32 v71, v38, 16, 1
	v_pk_mul_f32 v[40:41], v[80:81], v[72:73]
	v_lshrrev_b32_e32 v34, 16, v34
	v_lshrrev_b32_e32 v35, 16, v35
	v_add3_u32 v38, v38, v71, s62
	v_add3_u32 v39, v39, v70, s62
	v_bfe_u32 v68, v41, 16, 1
	v_bfe_u32 v69, v40, 16, 1
	v_and_or_b32 v35, v39, s63, v35
	v_and_or_b32 v34, v38, s63, v34
	v_mov_b32_e32 v39, s9
	v_or_b32_e32 v38, s8, v60
	v_lshrrev_b32_e32 v36, 16, v36
	v_lshrrev_b32_e32 v37, 16, v37
	v_add3_u32 v40, v40, v69, s62
	v_add3_u32 v41, v41, v68, s62
	v_lshlrev_b64 v[38:39], 13, v[38:39]
	v_and_or_b32 v37, v41, s63, v37
	v_and_or_b32 v36, v40, s63, v36
	v_lshl_add_u64 v[38:39], v[62:63], 0, v[38:39]
	global_store_dwordx4 v[38:39], v[34:37], off
	s_waitcnt lgkmcnt(0)
	s_add_i32 s35, s35, s59
	s_andn2_b64 vcc, exec, s[88:89]
	s_mov_b32 s66, s65
	s_cbranch_vccz .LBB0_975
.LBB0_910:
	s_ashr_i32 s8, s66, 31
	s_lshr_b32 s8, s8, 25
	s_add_i32 s8, s66, s8
	s_ashr_i32 s67, s8, 7
	s_lshl_b32 s90, s67, 6
	s_ashr_i32 s91, s90, 31
	s_waitcnt vmcnt(4)
	ds_write2_b32 v43, v2, v1 offset1:66
	ds_write2_b32 v43, v4, v3 offset0:132 offset1:198
	ds_write2_b32 v47, v6, v5 offset0:8 offset1:74
	ds_write2_b32 v47, v8, v7 offset0:140 offset1:206
	ds_write2_b32 v49, v10, v9 offset0:16 offset1:82
	ds_write2_b32 v49, v12, v11 offset0:148 offset1:214
	ds_write2_b32 v61, v14, v13 offset0:24 offset1:90
	ds_write2_b32 v61, v16, v15 offset0:156 offset1:222
	ds_write2_b32 v64, v18, v17 offset0:32 offset1:98
	ds_write2_b32 v64, v20, v19 offset0:164 offset1:230
	ds_write2_b32 v65, v22, v21 offset0:40 offset1:106
	ds_write2_b32 v65, v24, v23 offset0:172 offset1:238
	ds_write2_b32 v66, v26, v25 offset0:48 offset1:114
	ds_write2_b32 v66, v28, v27 offset0:180 offset1:246
	ds_write2_b32 v67, v30, v29 offset0:56 offset1:122
	ds_write2_b32 v67, v32, v31 offset0:188 offset1:254
	v_lshl_add_u64 v[34:35], s[90:91], 2, v[52:53]
	global_load_dwordx4 v[38:41], v[34:35], off offset:16
	s_nop 0
	global_load_dwordx4 v[34:37], v[34:35], off
	s_add_i32 s65, s66, s58
	s_cmpk_gt_i32 s65, 0x1fff
	s_cselect_b64 s[88:89], -1, 0
	s_and_b64 vcc, exec, s[88:89]
	s_cbranch_vccnz .Lcvt_last_3
	s_ashr_i32 s8, s65, 31
	s_lshr_b32 s8, s8, 25
	s_add_i32 s8, s65, s8
	s_ashr_i32 s69, s8, 7
	s_lshl_b32 s8, s69, 12
	s_sub_i32 s68, s35, s8
	v_add_u32_e32 v1, s68, v184
	s_movk_i32 s8, 0x1000
	v_cmp_gt_i32_e64 s[8:9], s8, v1
	v_lshl_or_b32 v1, s69, 6, v45
	v_mov_b64_e32 v[2:3], s[86:87]
	s_mov_b32 s69, 0xc000
	v_mad_i64_i32 v[2:3], s[70:71], v1, s69, v[2:3]
	s_ashr_i32 s69, s68, 31
	v_lshl_add_u64 v[2:3], s[68:69], 2, v[2:3]
	v_lshl_add_u64 v[62:63], v[2:3], 0, v[50:51]
	v_mov_b32_e32 v1, 0
	v_mov_b32_e32 v2, 0
	s_and_saveexec_b64 s[92:93], s[8:9]
	s_cbranch_execz .LBB0_913
	global_load_dword v2, v[62:63], off

.LBB0_1046:
	s_lshl_b32 s8, s69, 7
	s_sub_i32 s68, s68, s8
	s_bfe_i32 s8, s68, 0x80000
	s_bfe_u32 s8, s8, 0x2000d
	s_waitcnt lgkmcnt(0)
	s_add_i32 s8, s68, s8
	s_lshl_b32 s68, s68, 5
	s_sext_i32_i16 s69, s68
	ds_read2_b32 v[72:73], v33 offset0:231 offset1:239
	ds_read2_b32 v[74:75], v33 offset0:165 offset1:173
	ds_read2_b32 v[76:77], v33 offset0:198 offset1:206
	ds_read2_b32 v[78:79], v33 offset0:132 offset1:140
	ds_read2_b32 v[82:83], v33 offset0:99 offset1:107
	ds_read2_b32 v[84:85], v33 offset0:33 offset1:41
	ds_read2_b32 v[86:87], v33 offset0:66 offset1:74
	ds_read2_b32 v[90:91], v33 offset1:8
	s_bfe_u32 s69, s69, 0x70018
	s_sext_i32_i8 s8, s8
	s_add_i32 s69, s68, s69
	s_lshr_b32 s8, s8, 2
	s_and_b32 s69, s69, 0xff80
	s_bfe_i64 s[8:9], s[8:9], 0x100000
	s_sub_i32 s68, s68, s69
	s_lshl_b64 s[8:9], s[8:9], 8
	s_bfe_i64 s[68:69], s[68:69], 0x100000
	s_waitcnt vmcnt(33)
	v_mov_b32_e32 v80, v39
	v_mov_b32_e32 v81, v41
	v_mov_b32_e32 v39, v40
	s_waitcnt lgkmcnt(4)
	v_mov_b32_e32 v40, v78
	v_mov_b32_e32 v41, v76
	s_waitcnt vmcnt(32)
	v_mov_b32_e32 v88, v35
	v_mov_b32_e32 v89, v37
	v_mov_b32_e32 v35, v36
	s_waitcnt lgkmcnt(0)
	v_mov_b32_e32 v36, v90
	v_mov_b32_e32 v37, v86
	s_add_u32 s8, s68, s8
	v_mov_b32_e32 v68, v74
	v_mov_b32_e32 v69, v72
	v_pk_mul_f32 v[40:41], v[38:39], v[40:41]
	v_mov_b32_e32 v70, v84
	v_mov_b32_e32 v71, v82
	v_pk_mul_f32 v[36:37], v[34:35], v[36:37]
	s_addc_u32 s9, s69, s9
	v_pk_mul_f32 v[68:69], v[80:81], v[68:69]
	v_pk_mul_f32 v[70:71], v[88:89], v[70:71]
	v_bfe_u32 v72, v36, 16, 1
	v_bfe_u32 v74, v37, 16, 1
	v_bfe_u32 v76, v40, 16, 1
	v_bfe_u32 v78, v41, 16, 1
	s_add_u32 s8, s8, 0x80
	v_add3_u32 v41, v41, v78, s65
	v_add3_u32 v40, v40, v76, s65
	v_add3_u32 v37, v37, v74, s65
	v_add3_u32 v36, v36, v72, s65
	v_bfe_u32 v72, v69, 16, 1
	v_bfe_u32 v74, v68, 16, 1
	v_bfe_u32 v76, v71, 16, 1
	v_bfe_u32 v78, v70, 16, 1
	s_addc_u32 s9, s9, 0
	v_lshrrev_b32_e32 v36, 16, v36
	v_lshrrev_b32_e32 v37, 16, v37
	v_lshrrev_b32_e32 v40, 16, v40
	v_lshrrev_b32_e32 v41, 16, v41
	v_add3_u32 v78, v70, v78, s65
	v_add3_u32 v76, v71, v76, s65
	v_add3_u32 v68, v68, v74, s65
	v_add3_u32 v69, v69, v72, s65
	v_and_or_b32 v71, v69, s66, v41
	v_and_or_b32 v70, v68, s66, v40
	v_and_or_b32 v69, v76, s66, v37
	v_and_or_b32 v68, v78, s66, v36
	v_mov_b32_e32 v37, s9
	v_or_b32_e32 v36, s8, v44
	v_lshl_add_u64 v[62:63], s[16:17], 1, v[54:55]
	v_lshlrev_b64 v[36:37], 13, v[36:37]
	v_lshl_add_u64 v[36:37], v[62:63], 0, v[36:37]
	v_mov_b32_e32 v86, v91
	global_store_dwordx4 v[36:37], v[68:71], off
	v_mov_b32_e32 v72, v75
	v_mov_b32_e32 v76, v79
	v_pk_mul_f32 v[70:71], v[34:35], v[86:87]
	v_pk_mul_f32 v[36:37], v[80:81], v[72:73]
	v_pk_mul_f32 v[40:41], v[38:39], v[76:77]
	v_bfe_u32 v72, v70, 16, 1
	v_bfe_u32 v73, v71, 16, 1
	v_bfe_u32 v74, v40, 16, 1
	v_bfe_u32 v75, v41, 16, 1
	v_add3_u32 v71, v71, v73, s65
	v_add3_u32 v70, v70, v72, s65
	v_mov_b32_e32 v82, v85
	v_add3_u32 v41, v41, v75, s65
	v_add3_u32 v40, v40, v74, s65
	v_lshrrev_b32_e32 v72, 16, v70
	v_lshrrev_b32_e32 v73, 16, v71
	v_bfe_u32 v70, v37, 16, 1
	v_bfe_u32 v71, v36, 16, 1
	v_pk_mul_f32 v[68:69], v[88:89], v[82:83]
	v_lshrrev_b32_e32 v40, 16, v40
	v_lshrrev_b32_e32 v41, 16, v41
	v_add3_u32 v36, v36, v71, s65
	v_add3_u32 v37, v37, v70, s65
	v_bfe_u32 v74, v69, 16, 1
	v_bfe_u32 v75, v68, 16, 1
	v_and_or_b32 v71, v37, s66, v41
	v_and_or_b32 v70, v36, s66, v40
	v_mov_b32_e32 v37, s9
	v_or_b32_e32 v36, s8, v56
	v_add3_u32 v68, v68, v75, s65
	v_add3_u32 v69, v69, v74, s65
	v_lshlrev_b64 v[36:37], 13, v[36:37]
	v_and_or_b32 v69, v69, s66, v73
	v_and_or_b32 v68, v68, s66, v72
	v_lshl_add_u64 v[36:37], v[62:63], 0, v[36:37]
	ds_read2_b32 v[40:41], v33 offset0:181 offset1:189
	ds_read2_b32 v[72:73], v33 offset0:247 offset1:255
	global_store_dwordx4 v[36:37], v[68:71], off
	ds_read2_b32 v[36:37], v33 offset0:148 offset1:156
	ds_read2_b32 v[74:75], v33 offset0:214 offset1:222
	ds_read2_b32 v[76:77], v33 offset0:49 offset1:57
	ds_read2_b32 v[78:79], v33 offset0:115 offset1:123
	ds_read2_b32 v[82:83], v33 offset0:16 offset1:24
	ds_read2_b32 v[84:85], v33 offset0:82 offset1:90
	s_waitcnt lgkmcnt(7)
	v_mov_b32_e32 v68, v40
	s_waitcnt lgkmcnt(5)
	v_mov_b32_e32 v70, v36
	s_waitcnt lgkmcnt(4)
	v_mov_b32_e32 v71, v74
	s_waitcnt lgkmcnt(3)
	v_mov_b32_e32 v86, v76
	s_waitcnt lgkmcnt(2)
	v_mov_b32_e32 v87, v78
	s_waitcnt lgkmcnt(1)
	v_mov_b32_e32 v90, v82
	s_waitcnt lgkmcnt(0)
	v_mov_b32_e32 v91, v84
	v_mov_b32_e32 v69, v72
	v_pk_mul_f32 v[70:71], v[38:39], v[70:71]
	v_pk_mul_f32 v[86:87], v[88:89], v[86:87]
	v_pk_mul_f32 v[90:91], v[34:35], v[90:91]
	v_pk_mul_f32 v[68:69], v[80:81], v[68:69]
	v_bfe_u32 v36, v90, 16, 1
	v_bfe_u32 v40, v91, 16, 1
	v_bfe_u32 v72, v70, 16, 1
	v_bfe_u32 v74, v71, 16, 1
	v_bfe_u32 v76, v87, 16, 1
	v_bfe_u32 v78, v86, 16, 1
	v_add3_u32 v71, v71, v74, s65
	v_add3_u32 v70, v70, v72, s65
	v_add3_u32 v40, v91, v40, s65
	v_add3_u32 v36, v90, v36, s65
	v_bfe_u32 v72, v69, 16, 1
	v_bfe_u32 v74, v68, 16, 1
	v_add3_u32 v78, v86, v78, s65
	v_add3_u32 v76, v87, v76, s65
	v_mov_b32_e32 v87, s9
	v_or_b32_e32 v86, s8, v58
	v_lshrrev_b32_e32 v36, 16, v36
	v_lshrrev_b32_e32 v40, 16, v40
	v_lshrrev_b32_e32 v70, 16, v70
	v_lshrrev_b32_e32 v71, 16, v71
	v_add3_u32 v68, v68, v74, s65
	v_add3_u32 v69, v69, v72, s65
	v_lshlrev_b64 v[86:87], 13, v[86:87]
	v_mov_b32_e32 v74, v37
	v_mov_b32_e32 v84, v83
	v_and_or_b32 v71, v69, s66, v71
	v_and_or_b32 v70, v68, s66, v70
	v_and_or_b32 v69, v76, s66, v40
	v_and_or_b32 v68, v78, s66, v36
	v_lshl_add_u64 v[86:87], v[62:63], 0, v[86:87]
	v_pk_mul_f32 v[36:37], v[38:39], v[74:75]
	v_mov_b32_e32 v78, v77
	v_pk_mul_f32 v[34:35], v[34:35], v[84:85]
	global_store_dwordx4 v[86:87], v[68:71], off
	v_pk_mul_f32 v[38:39], v[88:89], v[78:79]
	v_mov_b32_e32 v72, v41
	v_bfe_u32 v68, v34, 16, 1
	v_bfe_u32 v69, v35, 16, 1
	v_bfe_u32 v70, v36, 16, 1
	v_bfe_u32 v71, v37, 16, 1
	v_add3_u32 v37, v37, v71, s65
	v_add3_u32 v36, v36, v70, s65
	v_add3_u32 v35, v35, v69, s65
	v_add3_u32 v34, v34, v68, s65
	v_bfe_u32 v70, v39, 16, 1
	v_bfe_u32 v71, v38, 16, 1
	v_pk_mul_f32 v[40:41], v[80:81], v[72:73]
	v_lshrrev_b32_e32 v34, 16, v34
	v_lshrrev_b32_e32 v35, 16, v35
	v_add3_u32 v38, v38, v71, s65
	v_add3_u32 v39, v39, v70, s65
	v_bfe_u32 v68, v41, 16, 1
	v_bfe_u32 v69, v40, 16, 1
	v_and_or_b32 v35, v39, s66, v35
	v_and_or_b32 v34, v38, s66, v34
	v_mov_b32_e32 v39, s9
	v_or_b32_e32 v38, s8, v60
	v_lshrrev_b32_e32 v36, 16, v36
	v_lshrrev_b32_e32 v37, 16, v37
	v_add3_u32 v40, v40, v69, s65
	v_add3_u32 v41, v41, v68, s65
	v_lshlrev_b64 v[38:39], 13, v[38:39]
	v_and_or_b32 v37, v41, s66, v37
	v_and_or_b32 v36, v40, s66, v36
	v_lshl_add_u64 v[38:39], v[62:63], 0, v[38:39]
	global_store_dwordx4 v[38:39], v[34:37], off
	s_waitcnt lgkmcnt(0)
	s_add_i32 s35, s35, s59
	s_andn2_b64 vcc, exec, s[0:1]
	s_mov_b32 s68, s67
	s_cbranch_vccz .LBB0_1113
.LBB0_1047:
	s_ashr_i32 s0, s68, 31
	s_lshr_b32 s0, s0, 25
	s_add_i32 s0, s68, s0
	s_ashr_i32 s69, s0, 7
	s_lshl_b32 s16, s69, 6
	s_ashr_i32 s17, s16, 31
	s_waitcnt vmcnt(4)
	ds_write2_b32 v43, v2, v1 offset1:66
	ds_write2_b32 v43, v4, v3 offset0:132 offset1:198
	ds_write2_b32 v47, v6, v5 offset0:8 offset1:74
	ds_write2_b32 v47, v8, v7 offset0:140 offset1:206
	ds_write2_b32 v49, v10, v9 offset0:16 offset1:82
	ds_write2_b32 v49, v12, v11 offset0:148 offset1:214
	ds_write2_b32 v61, v14, v13 offset0:24 offset1:90
	ds_write2_b32 v61, v16, v15 offset0:156 offset1:222
	ds_write2_b32 v64, v18, v17 offset0:32 offset1:98
	ds_write2_b32 v64, v20, v19 offset0:164 offset1:230
	ds_write2_b32 v65, v22, v21 offset0:40 offset1:106
	ds_write2_b32 v65, v24, v23 offset0:172 offset1:238
	ds_write2_b32 v66, v26, v25 offset0:48 offset1:114
	ds_write2_b32 v66, v28, v27 offset0:180 offset1:246
	ds_write2_b32 v67, v30, v29 offset0:56 offset1:122
	ds_write2_b32 v67, v32, v31 offset0:188 offset1:254
	v_lshl_add_u64 v[34:35], s[16:17], 2, v[52:53]
	global_load_dwordx4 v[38:41], v[34:35], off offset:16
	s_nop 0
	global_load_dwordx4 v[34:37], v[34:35], off
	s_add_i32 s67, s68, s58
	s_cmpk_gt_i32 s67, 0x1fff
	s_cselect_b64 s[0:1], -1, 0
	s_and_b64 vcc, exec, s[0:1]
	s_cbranch_vccnz .Lcvt_last_2
	s_ashr_i32 s8, s67, 31
	s_lshr_b32 s8, s8, 25
	s_add_i32 s8, s67, s8
	s_ashr_i32 s71, s8, 7
	s_lshl_b32 s8, s71, 12
	s_sub_i32 s70, s35, s8
	v_add_u32_e32 v1, s70, v184
	v_cmp_gt_i32_e64 s[8:9], s62, v1
	v_lshl_or_b32 v1, s71, 6, v45
	v_mov_b64_e32 v[2:3], s[18:19]
	v_mad_i64_i32 v[2:3], s[72:73], v1, s63, v[2:3]
	s_ashr_i32 s71, s70, 31
	v_lshl_add_u64 v[2:3], s[70:71], 2, v[2:3]
	v_lshl_add_u64 v[62:63], v[2:3], 0, v[50:51]
	v_mov_b32_e32 v1, 0
	v_mov_b32_e32 v2, 0
	s_and_saveexec_b64 s[84:85], s[8:9]
	s_cbranch_execz .LBB0_1050
	global_load_dword v2, v[62:63], off

.LBB0_1317:
	s_mulk_i32 s65, 0xfea8
	s_waitcnt lgkmcnt(0)
	s_add_i32 s22, s63, s65
	s_bfe_u32 s4, s22, 0x2001d
	ds_read2_b32 v[72:73], v33 offset0:231 offset1:239
	ds_read2_b32 v[74:75], v33 offset0:165 offset1:173
	ds_read2_b32 v[76:77], v33 offset0:198 offset1:206
	ds_read2_b32 v[78:79], v33 offset0:132 offset1:140
	ds_read2_b32 v[82:83], v33 offset0:99 offset1:107
	ds_read2_b32 v[84:85], v33 offset0:33 offset1:41
	ds_read2_b32 v[86:87], v33 offset0:66 offset1:74
	ds_read2_b32 v[90:91], v33 offset1:8
	s_add_i32 s4, s22, s4
	s_lshl_b32 s22, s22, 5
	s_sext_i32_i16 s23, s22
	s_bfe_u32 s23, s23, 0x70018
	s_sext_i32_i16 s4, s4
	s_add_i32 s23, s22, s23
	s_lshr_b32 s4, s4, 2
	s_and_b32 s23, s23, 0xff80
	s_waitcnt vmcnt(33)
	v_mov_b32_e32 v80, v39
	v_mov_b32_e32 v81, v41
	v_mov_b32_e32 v39, v40
	s_waitcnt lgkmcnt(4)
	v_mov_b32_e32 v40, v78
	v_mov_b32_e32 v41, v76
	s_waitcnt vmcnt(32)
	v_mov_b32_e32 v88, v35
	v_mov_b32_e32 v89, v37
	v_mov_b32_e32 v35, v36
	s_waitcnt lgkmcnt(0)
	v_mov_b32_e32 v36, v90
	v_mov_b32_e32 v37, v86
	s_bfe_i64 s[4:5], s[4:5], 0x100000
	s_sub_i32 s22, s22, s23
	v_mov_b32_e32 v68, v74
	v_mov_b32_e32 v69, v72
	v_pk_mul_f32 v[40:41], v[38:39], v[40:41]
	v_mov_b32_e32 v70, v84
	v_mov_b32_e32 v71, v82
	v_pk_mul_f32 v[36:37], v[34:35], v[36:37]
	s_bfe_i64 s[22:23], s[22:23], 0x100000
	s_lshl_b64 s[4:5], s[4:5], 8
	v_pk_mul_f32 v[68:69], v[80:81], v[68:69]
	v_pk_mul_f32 v[70:71], v[88:89], v[70:71]
	v_bfe_u32 v72, v36, 16, 1
	v_bfe_u32 v74, v37, 16, 1
	v_bfe_u32 v76, v40, 16, 1
	v_bfe_u32 v78, v41, 16, 1
	s_add_u32 s4, s4, s22
	v_add3_u32 v41, v41, v78, s43
	v_add3_u32 v40, v40, v76, s43
	v_add3_u32 v37, v37, v74, s43
	v_add3_u32 v36, v36, v72, s43
	v_bfe_u32 v72, v69, 16, 1
	v_bfe_u32 v74, v68, 16, 1
	v_bfe_u32 v76, v71, 16, 1
	v_bfe_u32 v78, v70, 16, 1
	s_addc_u32 s5, s5, s23
	v_lshrrev_b32_e32 v36, 16, v36
	v_lshrrev_b32_e32 v37, 16, v37
	v_lshrrev_b32_e32 v40, 16, v40
	v_lshrrev_b32_e32 v41, 16, v41
	v_add3_u32 v78, v70, v78, s43
	v_add3_u32 v76, v71, v76, s43
	v_add3_u32 v68, v68, v74, s43
	v_add3_u32 v69, v69, v72, s43
	v_and_or_b32 v71, v69, s59, v41
	v_and_or_b32 v70, v68, s59, v40
	v_and_or_b32 v69, v76, s59, v37
	v_and_or_b32 v68, v78, s59, v36
	v_mov_b32_e32 v37, s5
	v_or_b32_e32 v36, s4, v44
	v_lshl_add_u64 v[62:63], s[18:19], 1, v[54:55]
	v_lshlrev_b64 v[36:37], 13, v[36:37]
	v_lshl_add_u64 v[36:37], v[62:63], 0, v[36:37]
	v_mov_b32_e32 v86, v91
	global_store_dwordx4 v[36:37], v[68:71], off
	v_mov_b32_e32 v72, v75
	v_mov_b32_e32 v76, v79
	v_pk_mul_f32 v[70:71], v[34:35], v[86:87]
	v_pk_mul_f32 v[36:37], v[80:81], v[72:73]
	v_pk_mul_f32 v[40:41], v[38:39], v[76:77]
	v_bfe_u32 v72, v70, 16, 1
	v_bfe_u32 v73, v71, 16, 1
	v_bfe_u32 v74, v40, 16, 1
	v_bfe_u32 v75, v41, 16, 1
	v_add3_u32 v71, v71, v73, s43
	v_add3_u32 v70, v70, v72, s43
	v_mov_b32_e32 v82, v85
	v_add3_u32 v41, v41, v75, s43
	v_add3_u32 v40, v40, v74, s43
	v_lshrrev_b32_e32 v72, 16, v70
	v_lshrrev_b32_e32 v73, 16, v71
	v_bfe_u32 v70, v37, 16, 1
	v_bfe_u32 v71, v36, 16, 1
	v_pk_mul_f32 v[68:69], v[88:89], v[82:83]
	v_lshrrev_b32_e32 v40, 16, v40
	v_lshrrev_b32_e32 v41, 16, v41
	v_add3_u32 v36, v36, v71, s43
	v_add3_u32 v37, v37, v70, s43
	v_bfe_u32 v74, v69, 16, 1
	v_bfe_u32 v75, v68, 16, 1
	v_and_or_b32 v71, v37, s59, v41
	v_and_or_b32 v70, v36, s59, v40
	v_mov_b32_e32 v37, s5
	v_or_b32_e32 v36, s4, v56
	v_add3_u32 v68, v68, v75, s43
	v_add3_u32 v69, v69, v74, s43
	v_lshlrev_b64 v[36:37], 13, v[36:37]
	v_and_or_b32 v69, v69, s59, v73
	v_and_or_b32 v68, v68, s59, v72
	v_lshl_add_u64 v[36:37], v[62:63], 0, v[36:37]
	ds_read2_b32 v[40:41], v33 offset0:181 offset1:189
	ds_read2_b32 v[72:73], v33 offset0:247 offset1:255
	global_store_dwordx4 v[36:37], v[68:71], off
	ds_read2_b32 v[36:37], v33 offset0:148 offset1:156
	ds_read2_b32 v[74:75], v33 offset0:214 offset1:222
	ds_read2_b32 v[76:77], v33 offset0:49 offset1:57
	ds_read2_b32 v[78:79], v33 offset0:115 offset1:123
	ds_read2_b32 v[82:83], v33 offset0:16 offset1:24
	ds_read2_b32 v[84:85], v33 offset0:82 offset1:90
	s_waitcnt lgkmcnt(7)
	v_mov_b32_e32 v68, v40
	s_waitcnt lgkmcnt(5)
	v_mov_b32_e32 v70, v36
	s_waitcnt lgkmcnt(4)
	v_mov_b32_e32 v71, v74
	s_waitcnt lgkmcnt(3)
	v_mov_b32_e32 v86, v76
	s_waitcnt lgkmcnt(2)
	v_mov_b32_e32 v87, v78
	s_waitcnt lgkmcnt(1)
	v_mov_b32_e32 v90, v82
	s_waitcnt lgkmcnt(0)
	v_mov_b32_e32 v91, v84
	v_mov_b32_e32 v69, v72
	v_pk_mul_f32 v[70:71], v[38:39], v[70:71]
	v_pk_mul_f32 v[86:87], v[88:89], v[86:87]
	v_pk_mul_f32 v[90:91], v[34:35], v[90:91]
	v_pk_mul_f32 v[68:69], v[80:81], v[68:69]
	v_bfe_u32 v36, v90, 16, 1
	v_bfe_u32 v40, v91, 16, 1
	v_bfe_u32 v72, v70, 16, 1
	v_bfe_u32 v74, v71, 16, 1
	v_bfe_u32 v76, v87, 16, 1
	v_bfe_u32 v78, v86, 16, 1
	v_add3_u32 v71, v71, v74, s43
	v_add3_u32 v70, v70, v72, s43
	v_add3_u32 v40, v91, v40, s43
	v_add3_u32 v36, v90, v36, s43
	v_bfe_u32 v72, v69, 16, 1
	v_bfe_u32 v74, v68, 16, 1
	v_add3_u32 v78, v86, v78, s43
	v_add3_u32 v76, v87, v76, s43
	v_mov_b32_e32 v87, s5
	v_or_b32_e32 v86, s4, v58
	v_lshrrev_b32_e32 v36, 16, v36
	v_lshrrev_b32_e32 v40, 16, v40
	v_lshrrev_b32_e32 v70, 16, v70
	v_lshrrev_b32_e32 v71, 16, v71
	v_add3_u32 v68, v68, v74, s43
	v_add3_u32 v69, v69, v72, s43
	v_lshlrev_b64 v[86:87], 13, v[86:87]
	v_mov_b32_e32 v74, v37
	v_mov_b32_e32 v84, v83
	v_and_or_b32 v71, v69, s59, v71
	v_and_or_b32 v70, v68, s59, v70
	v_and_or_b32 v69, v76, s59, v40
	v_and_or_b32 v68, v78, s59, v36
	v_lshl_add_u64 v[86:87], v[62:63], 0, v[86:87]
	v_pk_mul_f32 v[36:37], v[38:39], v[74:75]
	v_mov_b32_e32 v78, v77
	v_pk_mul_f32 v[34:35], v[34:35], v[84:85]
	global_store_dwordx4 v[86:87], v[68:71], off
	v_pk_mul_f32 v[38:39], v[88:89], v[78:79]
	v_mov_b32_e32 v72, v41
	v_bfe_u32 v68, v34, 16, 1
	v_bfe_u32 v69, v35, 16, 1
	v_bfe_u32 v70, v36, 16, 1
	v_bfe_u32 v71, v37, 16, 1
	v_add3_u32 v37, v37, v71, s43
	v_add3_u32 v36, v36, v70, s43
	v_add3_u32 v35, v35, v69, s43
	v_add3_u32 v34, v34, v68, s43
	v_bfe_u32 v70, v39, 16, 1
	v_bfe_u32 v71, v38, 16, 1
	v_pk_mul_f32 v[40:41], v[80:81], v[72:73]
	v_lshrrev_b32_e32 v34, 16, v34
	v_lshrrev_b32_e32 v35, 16, v35
	v_add3_u32 v38, v38, v71, s43
	v_add3_u32 v39, v39, v70, s43
	v_bfe_u32 v68, v41, 16, 1
	v_bfe_u32 v69, v40, 16, 1
	v_and_or_b32 v35, v39, s59, v35
	v_and_or_b32 v34, v38, s59, v34
	v_mov_b32_e32 v39, s5
	v_or_b32_e32 v38, s4, v60
	v_lshrrev_b32_e32 v36, 16, v36
	v_lshrrev_b32_e32 v37, 16, v37
	v_add3_u32 v40, v40, v69, s43
	v_add3_u32 v41, v41, v68, s43
	v_lshlrev_b64 v[38:39], 13, v[38:39]
	v_and_or_b32 v37, v41, s59, v37
	v_and_or_b32 v36, v40, s59, v36
	v_lshl_add_u64 v[38:39], v[62:63], 0, v[38:39]
	global_store_dwordx4 v[38:39], v[34:37], off
	s_waitcnt lgkmcnt(0)
	s_add_i32 s24, s24, s25
	s_andn2_b64 vcc, exec, s[16:17]
	s_mov_b32 s63, s62
	s_cbranch_vccz .LBB0_1383
.LBB0_1318:
	s_mul_hi_i32 s4, s63, 0x2fa0be83
	s_lshr_b32 s5, s4, 31
	s_ashr_i32 s65, s4, 6
	s_add_i32 s65, s65, s5
	s_lshl_b32 s18, s65, 6
	s_ashr_i32 s19, s18, 31
	s_waitcnt vmcnt(4)
	ds_write2_b32 v43, v2, v1 offset1:66
	ds_write2_b32 v43, v4, v3 offset0:132 offset1:198
	ds_write2_b32 v47, v6, v5 offset0:8 offset1:74
	ds_write2_b32 v47, v8, v7 offset0:140 offset1:206
	ds_write2_b32 v49, v10, v9 offset0:16 offset1:82
	ds_write2_b32 v49, v12, v11 offset0:148 offset1:214
	ds_write2_b32 v61, v14, v13 offset0:24 offset1:90
	ds_write2_b32 v61, v16, v15 offset0:156 offset1:222
	ds_write2_b32 v64, v18, v17 offset0:32 offset1:98
	ds_write2_b32 v64, v20, v19 offset0:164 offset1:230
	ds_write2_b32 v65, v22, v21 offset0:40 offset1:106
	ds_write2_b32 v65, v24, v23 offset0:172 offset1:238
	ds_write2_b32 v66, v26, v25 offset0:48 offset1:114
	ds_write2_b32 v66, v28, v27 offset0:180 offset1:246
	ds_write2_b32 v67, v30, v29 offset0:56 offset1:122
	ds_write2_b32 v67, v32, v31 offset0:188 offset1:254
	v_lshl_add_u64 v[34:35], s[18:19], 2, v[52:53]
	global_load_dwordx4 v[38:41], v[34:35], off offset:16
	s_nop 0
	global_load_dwordx4 v[34:37], v[34:35], off
	s_add_i32 s62, s63, s58
	s_cmpk_gt_i32 s62, 0x55ff
	s_cselect_b64 s[16:17], -1, 0
	s_and_b64 vcc, exec, s[16:17]
	s_cbranch_vccnz .Lcvt_last_1
	s_mul_hi_i32 s4, s62, 0x2fa0be83
	s_lshr_b32 s5, s4, 31
	s_ashr_i32 s4, s4, 6
	s_add_i32 s23, s4, s5
	s_mul_i32 s4, s23, 0xffffd500
	s_add_i32 s22, s24, s4
	v_add_u32_e32 v1, s22, v184
	v_cmp_gt_i32_e64 s[4:5], s35, v1
	v_lshl_or_b32 v1, s23, 6, v45
	v_mov_b64_e32 v[2:3], s[8:9]
	v_mad_i64_i32 v[2:3], s[66:67], v1, s42, v[2:3]
	s_ashr_i32 s23, s22, 31
	v_lshl_add_u64 v[2:3], s[22:23], 2, v[2:3]
	v_lshl_add_u64 v[62:63], v[2:3], 0, v[50:51]
	v_mov_b32_e32 v1, 0
	v_mov_b32_e32 v2, 0
	s_and_saveexec_b64 s[22:23], s[4:5]
	s_cbranch_execz .LBB0_1321
	global_load_dword v2, v[62:63], off

.LBB0_1452:
	s_mulk_i32 s42, 0xfea8
	s_add_i32 s18, s35, s42
	s_bfe_u32 s4, s18, 0x2001d
	s_waitcnt lgkmcnt(0)
	s_add_i32 s4, s18, s4
	s_lshl_b32 s18, s18, 5
	s_sext_i32_i16 s19, s18
	ds_read2_b32 v[72:73], v33 offset0:231 offset1:239
	ds_read2_b32 v[74:75], v33 offset0:165 offset1:173
	ds_read2_b32 v[76:77], v33 offset0:198 offset1:206
	ds_read2_b32 v[78:79], v33 offset0:132 offset1:140
	ds_read2_b32 v[82:83], v33 offset0:99 offset1:107
	ds_read2_b32 v[84:85], v33 offset0:33 offset1:41
	ds_read2_b32 v[86:87], v33 offset0:66 offset1:74
	ds_read2_b32 v[90:91], v33 offset1:8
	s_bfe_u32 s19, s19, 0x70018
	s_sext_i32_i16 s4, s4
	s_add_i32 s19, s18, s19
	s_lshr_b32 s4, s4, 2
	s_and_b32 s19, s19, 0xff80
	s_bfe_i64 s[4:5], s[4:5], 0x100000
	s_sub_i32 s18, s18, s19
	s_lshl_b64 s[4:5], s[4:5], 8
	s_bfe_i64 s[18:19], s[18:19], 0x100000
	s_waitcnt vmcnt(33)
	v_mov_b32_e32 v80, v39
	v_mov_b32_e32 v81, v41
	v_mov_b32_e32 v39, v40
	s_waitcnt lgkmcnt(4)
	v_mov_b32_e32 v40, v78
	v_mov_b32_e32 v41, v76
	s_waitcnt vmcnt(32)
	v_mov_b32_e32 v88, v35
	v_mov_b32_e32 v89, v37
	v_mov_b32_e32 v35, v36
	s_waitcnt lgkmcnt(0)
	v_mov_b32_e32 v36, v90
	v_mov_b32_e32 v37, v86
	s_add_u32 s4, s18, s4
	v_mov_b32_e32 v68, v74
	v_mov_b32_e32 v69, v72
	v_pk_mul_f32 v[40:41], v[38:39], v[40:41]
	v_mov_b32_e32 v70, v84
	v_mov_b32_e32 v71, v82
	v_pk_mul_f32 v[36:37], v[34:35], v[36:37]
	s_addc_u32 s5, s19, s5
	v_pk_mul_f32 v[68:69], v[80:81], v[68:69]
	v_pk_mul_f32 v[70:71], v[88:89], v[70:71]
	v_bfe_u32 v67, v36, 16, 1
	v_bfe_u32 v72, v37, 16, 1
	v_bfe_u32 v74, v40, 16, 1
	v_bfe_u32 v76, v41, 16, 1
	s_add_u32 s4, s4, 0x80
	v_add3_u32 v41, v41, v76, s26
	v_add3_u32 v40, v40, v74, s26
	v_add3_u32 v37, v37, v72, s26
	v_add3_u32 v36, v36, v67, s26
	v_bfe_u32 v72, v68, 16, 1
	v_bfe_u32 v74, v71, 16, 1
	v_bfe_u32 v76, v70, 16, 1
	s_addc_u32 s5, s5, 0
	v_lshrrev_b32_e32 v36, 16, v36
	v_lshrrev_b32_e32 v37, 16, v37
	v_lshrrev_b32_e32 v40, 16, v40
	v_bfe_u32 v67, v69, 16, 1
	v_add3_u32 v76, v70, v76, s26
	v_add3_u32 v74, v71, v74, s26
	v_add3_u32 v68, v68, v72, s26
	v_add3_u32 v67, v69, v67, s26
	v_and_or_b32 v70, v68, s27, v40
	v_and_or_b32 v69, v74, s27, v37
	v_and_or_b32 v68, v76, s27, v36
	v_mov_b32_e32 v37, s5
	v_or_b32_e32 v36, s4, v44
	v_lshl_add_u64 v[60:61], s[16:17], 1, v[52:53]
	v_lshrrev_b32_e32 v41, 16, v41
	v_lshlrev_b64 v[36:37], 13, v[36:37]
	v_and_or_b32 v71, v67, s27, v41
	v_lshl_add_u64 v[36:37], v[60:61], 0, v[36:37]
	v_mov_b32_e32 v86, v91
	global_store_dwordx4 v[36:37], v[68:71], off
	v_mov_b32_e32 v72, v75
	v_mov_b32_e32 v76, v79
	v_pk_mul_f32 v[70:71], v[34:35], v[86:87]
	v_pk_mul_f32 v[36:37], v[80:81], v[72:73]
	v_pk_mul_f32 v[40:41], v[38:39], v[76:77]
	v_bfe_u32 v72, v71, 16, 1
	v_bfe_u32 v67, v70, 16, 1
	v_bfe_u32 v73, v40, 16, 1
	v_bfe_u32 v74, v41, 16, 1
	v_add3_u32 v71, v71, v72, s26
	v_mov_b32_e32 v82, v85
	v_add3_u32 v41, v41, v74, s26
	v_add3_u32 v40, v40, v73, s26
	v_add3_u32 v67, v70, v67, s26
	v_lshrrev_b32_e32 v72, 16, v71
	v_bfe_u32 v70, v37, 16, 1
	v_bfe_u32 v71, v36, 16, 1
	v_pk_mul_f32 v[68:69], v[88:89], v[82:83]
	v_lshrrev_b32_e32 v40, 16, v40
	v_lshrrev_b32_e32 v41, 16, v41
	v_add3_u32 v36, v36, v71, s26
	v_add3_u32 v37, v37, v70, s26
	v_bfe_u32 v73, v69, 16, 1
	v_bfe_u32 v74, v68, 16, 1
	v_and_or_b32 v71, v37, s27, v41
	v_and_or_b32 v70, v36, s27, v40
	v_mov_b32_e32 v37, s5
	v_or_b32_e32 v36, s4, v54
	v_lshrrev_b32_e32 v67, 16, v67
	v_add3_u32 v68, v68, v74, s26
	v_add3_u32 v69, v69, v73, s26
	v_lshlrev_b64 v[36:37], 13, v[36:37]
	v_and_or_b32 v69, v69, s27, v72
	v_and_or_b32 v68, v68, s27, v67
	v_lshl_add_u64 v[36:37], v[60:61], 0, v[36:37]
	ds_read2_b32 v[40:41], v33 offset0:181 offset1:189
	ds_read2_b32 v[72:73], v33 offset0:247 offset1:255
	global_store_dwordx4 v[36:37], v[68:71], off
	ds_read2_b32 v[36:37], v33 offset0:148 offset1:156
	ds_read2_b32 v[74:75], v33 offset0:214 offset1:222
	ds_read2_b32 v[76:77], v33 offset0:49 offset1:57
	ds_read2_b32 v[78:79], v33 offset0:115 offset1:123
	ds_read2_b32 v[82:83], v33 offset0:16 offset1:24
	ds_read2_b32 v[84:85], v33 offset0:82 offset1:90
	s_waitcnt lgkmcnt(7)
	v_mov_b32_e32 v68, v40
	s_waitcnt lgkmcnt(5)
	v_mov_b32_e32 v70, v36
	s_waitcnt lgkmcnt(4)
	v_mov_b32_e32 v71, v74
	v_pk_mul_f32 v[70:71], v[38:39], v[70:71]
	s_waitcnt lgkmcnt(1)
	v_mov_b32_e32 v90, v82
	s_waitcnt lgkmcnt(0)
	v_mov_b32_e32 v91, v84
	v_mov_b32_e32 v69, v72
	v_mov_b32_e32 v86, v76
	v_mov_b32_e32 v87, v78
	v_pk_mul_f32 v[90:91], v[34:35], v[90:91]
	v_bfe_u32 v72, v71, 16, 1
	v_pk_mul_f32 v[68:69], v[80:81], v[68:69]
	v_pk_mul_f32 v[86:87], v[88:89], v[86:87]
	v_bfe_u32 v40, v91, 16, 1
	v_bfe_u32 v67, v70, 16, 1
	v_add3_u32 v71, v71, v72, s26
	v_bfe_u32 v36, v90, 16, 1
	v_add3_u32 v67, v70, v67, s26
	v_add3_u32 v40, v91, v40, s26
	v_lshrrev_b32_e32 v70, 16, v71
	v_bfe_u32 v71, v69, 16, 1
	v_bfe_u32 v74, v87, 16, 1
	v_bfe_u32 v76, v86, 16, 1
	v_add3_u32 v36, v90, v36, s26
	v_lshrrev_b32_e32 v40, 16, v40
	v_bfe_u32 v72, v68, 16, 1
	v_add3_u32 v76, v86, v76, s26
	v_add3_u32 v74, v87, v74, s26
	v_add3_u32 v69, v69, v71, s26
	v_mov_b32_e32 v87, s5
	v_or_b32_e32 v86, s4, v56
	v_lshrrev_b32_e32 v36, 16, v36
	v_lshrrev_b32_e32 v67, 16, v67
	v_add3_u32 v68, v68, v72, s26
	v_and_or_b32 v71, v69, s27, v70
	v_and_or_b32 v69, v74, s27, v40
	v_lshlrev_b64 v[86:87], 13, v[86:87]
	v_mov_b32_e32 v74, v37
	v_mov_b32_e32 v84, v83
	v_and_or_b32 v70, v68, s27, v67
	v_and_or_b32 v68, v76, s27, v36
	v_lshl_add_u64 v[86:87], v[60:61], 0, v[86:87]
	v_pk_mul_f32 v[36:37], v[38:39], v[74:75]
	v_mov_b32_e32 v78, v77
	v_pk_mul_f32 v[34:35], v[34:35], v[84:85]
	global_store_dwordx4 v[86:87], v[68:71], off
	v_pk_mul_f32 v[38:39], v[88:89], v[78:79]
	v_bfe_u32 v67, v34, 16, 1
	v_bfe_u32 v68, v35, 16, 1
	v_bfe_u32 v69, v36, 16, 1
	v_bfe_u32 v70, v37, 16, 1
	v_mov_b32_e32 v72, v41
	v_add3_u32 v37, v37, v70, s26
	v_add3_u32 v36, v36, v69, s26
	v_add3_u32 v35, v35, v68, s26
	v_add3_u32 v34, v34, v67, s26
	v_bfe_u32 v69, v39, 16, 1
	v_bfe_u32 v70, v38, 16, 1
	v_pk_mul_f32 v[40:41], v[80:81], v[72:73]
	v_lshrrev_b32_e32 v34, 16, v34
	v_lshrrev_b32_e32 v35, 16, v35
	v_add3_u32 v38, v38, v70, s26
	v_add3_u32 v39, v39, v69, s26
	v_bfe_u32 v67, v41, 16, 1
	v_bfe_u32 v68, v40, 16, 1
	v_and_or_b32 v35, v39, s27, v35
	v_and_or_b32 v34, v38, s27, v34
	v_mov_b32_e32 v39, s5
	v_or_b32_e32 v38, s4, v58
	v_lshrrev_b32_e32 v36, 16, v36
	v_lshrrev_b32_e32 v37, 16, v37
	v_add3_u32 v40, v40, v68, s26
	v_add3_u32 v41, v41, v67, s26
	v_lshlrev_b64 v[38:39], 13, v[38:39]
	v_and_or_b32 v37, v41, s27, v37
	v_and_or_b32 v36, v40, s27, v36
	v_lshl_add_u64 v[38:39], v[60:61], 0, v[38:39]
	global_store_dwordx4 v[38:39], v[34:37], off
	s_waitcnt lgkmcnt(0)
	s_add_i32 s22, s22, s23
	s_andn2_b64 vcc, exec, s[0:1]
	s_mov_b32 s35, s33
	s_cbranch_vccz .LBB0_1518
.LBB0_1453:
	s_mul_hi_i32 s0, s35, 0x2fa0be83
	s_lshr_b32 s1, s0, 31
	s_ashr_i32 s42, s0, 6
	s_add_i32 s42, s42, s1
	s_lshl_b32 s16, s42, 6
	s_ashr_i32 s17, s16, 31
	s_waitcnt vmcnt(4)
	ds_write2_b32 v43, v2, v1 offset1:66
	ds_write2_b32 v43, v4, v3 offset0:132 offset1:198
	ds_write2_b32 v47, v6, v5 offset0:8 offset1:74
	ds_write2_b32 v47, v8, v7 offset0:140 offset1:206
	ds_write2_b32 v55, v10, v9 offset0:16 offset1:82
	ds_write2_b32 v55, v12, v11 offset0:148 offset1:214
	ds_write2_b32 v62, v14, v13 offset0:24 offset1:90
	ds_write2_b32 v62, v16, v15 offset0:156 offset1:222
	ds_write2_b32 v63, v18, v17 offset0:32 offset1:98
	ds_write2_b32 v63, v20, v19 offset0:164 offset1:230
	ds_write2_b32 v64, v22, v21 offset0:40 offset1:106
	ds_write2_b32 v64, v24, v23 offset0:172 offset1:238
	ds_write2_b32 v65, v26, v25 offset0:48 offset1:114
	ds_write2_b32 v65, v28, v27 offset0:180 offset1:246
	ds_write2_b32 v66, v30, v29 offset0:56 offset1:122
	ds_write2_b32 v66, v32, v31 offset0:188 offset1:254
	v_lshl_add_u64 v[34:35], s[16:17], 2, v[50:51]
	global_load_dwordx4 v[38:41], v[34:35], off offset:16
	s_nop 0
	global_load_dwordx4 v[34:37], v[34:35], off
	s_add_i32 s33, s35, s58
	s_cmpk_gt_i32 s33, 0x55ff
	s_cselect_b64 s[0:1], -1, 0
	s_and_b64 vcc, exec, s[0:1]
	s_cbranch_vccnz .Lcvt_last_0
	s_mul_hi_i32 s4, s33, 0x2fa0be83
	s_lshr_b32 s5, s4, 31
	s_ashr_i32 s4, s4, 6
	s_add_i32 s19, s4, s5
	s_mul_i32 s4, s19, 0xffffd500
	s_add_i32 s18, s22, s4
	v_add_u32_e32 v1, s18, v184
	v_cmp_gt_i32_e64 s[4:5], s24, v1
	v_lshl_or_b32 v1, s19, 6, v45
	v_mov_b64_e32 v[2:3], s[8:9]
	v_mad_i64_i32 v[2:3], s[62:63], v1, s25, v[2:3]
	s_ashr_i32 s19, s18, 31
	v_lshl_add_u64 v[2:3], s[18:19], 2, v[2:3]
	v_lshl_add_u64 v[60:61], v[2:3], 0, v[48:49]
	v_mov_b32_e32 v1, 0
	v_mov_b32_e32 v2, 0
	s_and_saveexec_b64 s[18:19], s[4:5]
	s_cbranch_execz .LBB0_1456
	global_load_dword v2, v[60:61], off
